# attention task epilogue: the row-sum exchange between the two half-waves uses v_permlane32_swap instead of a ds_bpermute LDS round trip
# speedup vs baseline: 1.0036x; 1.0028x over previous
; __device__ __forceinline__ unsigned pk2(float lo, float hi) { const f32x2 v = {lo, hi}; return __builtin_bit_cast(unsigned, __builtin_convertvector(v, bf16v2_t)); }
; __device__ __forceinline__ void attn_all(KArgs& a, LAS unsigned char* lds, int l) {
;     ...
;         asm volatile("s_waitcnt vmcnt(0)" ::: "memory");
;         const float inv = 1.f / (lsum + __shfl_xor(lsum, 32));
;         bf16_t* op = OA + (size_t)qtok * 512 + h * 64 + 4 * g;
; #pragma unroll
;         for (int jq = 0; jq < 4; ++jq) {
;             u32x2 o0, o1; o0.x = pk2(O0[4 * jq] * inv, O0[4 * jq + 1] * inv); o0.y = pk2(O0[4 * jq + 2] * inv, O0[4 * jq + 3] * inv);
;             o1.x = pk2(O1[4 * jq] * inv, O1[4 * jq + 1] * inv); o1.y = pk2(O1[4 * jq + 2] * inv, O1[4 * jq + 3] * inv);
;             *(u32x2*)(op + 8 * jq) = o0; *(u32x2*)(op + 32 + 8 * jq) = o1;
;         }
.LBB0_492:
	v_and_b32_e32 v2, 64, v217
	v_xor_b32_e32 v0, 32, v217
	v_add_u32_e32 v2, 64, v2
	v_cmp_lt_i32_e32 vcc, v0, v2
	s_waitcnt vmcnt(0)
	s_add_i32 s18, s18, s34
	s_cmp_ge_i32 s18, s3
	v_mov_b32_e32 v0, v107
	v_mov_b32_e32 v2, v107
	s_nop 1
	v_permlane32_swap_b32 v0, v2
	v_add_f32_e32 v0, v0, v2
	v_div_scale_f32 v2, s[0:1], v0, v0, 1.0
	v_rcp_f32_e32 v3, v2
	v_div_scale_f32 v4, vcc, 1.0, v0, 1.0
	v_fma_f32 v5, -v2, v3, 1.0
	v_fmac_f32_e32 v3, v5, v3
	v_mul_f32_e32 v5, v4, v3
	v_fma_f32 v6, -v2, v5, v4
	v_fmac_f32_e32 v5, v6, v3
	v_fma_f32 v2, -v2, v5, v4
	v_div_fmas_f32 v2, v2, v3, v5
	v_div_fixup_f32 v0, v2, v0, 1.0
	v_pk_mul_f32 v[4:5], v[32:33], v[0:1] op_sel_hi:[1,0]
	v_pk_mul_f32 v[6:7], v[34:35], v[0:1] op_sel_hi:[1,0]
	v_lshlrev_b64 v[2:3], 10, v[110:111]
	v_cvt_pk_bf16_f32 v4, v4, v5
	v_cvt_pk_bf16_f32 v5, v6, v7
	v_pk_mul_f32 v[6:7], v[16:17], v[0:1] op_sel_hi:[1,0]
	v_pk_mul_f32 v[8:9], v[18:19], v[0:1] op_sel_hi:[1,0]
	v_lshl_add_u64 v[2:3], v[104:105], 0, v[2:3]
	v_cvt_pk_bf16_f32 v6, v6, v7
	v_cvt_pk_bf16_f32 v7, v8, v9
	global_store_dwordx2 v[2:3], v[4:5], off
	global_store_dwordx2 v[2:3], v[6:7], off offset:64
	v_pk_mul_f32 v[4:5], v[36:37], v[0:1] op_sel_hi:[1,0]
	v_pk_mul_f32 v[6:7], v[38:39], v[0:1] op_sel_hi:[1,0]
	v_cvt_pk_bf16_f32 v4, v4, v5
	v_cvt_pk_bf16_f32 v5, v6, v7
	v_pk_mul_f32 v[6:7], v[20:21], v[0:1] op_sel_hi:[1,0]
	v_pk_mul_f32 v[8:9], v[22:23], v[0:1] op_sel_hi:[1,0]
	v_cvt_pk_bf16_f32 v6, v6, v7
	v_cvt_pk_bf16_f32 v7, v8, v9
	global_store_dwordx2 v[2:3], v[4:5], off offset:16
	global_store_dwordx2 v[2:3], v[6:7], off offset:80
	v_pk_mul_f32 v[4:5], v[40:41], v[0:1] op_sel_hi:[1,0]
	v_pk_mul_f32 v[6:7], v[42:43], v[0:1] op_sel_hi:[1,0]
	v_cvt_pk_bf16_f32 v4, v4, v5
	v_cvt_pk_bf16_f32 v5, v6, v7
	v_pk_mul_f32 v[6:7], v[24:25], v[0:1] op_sel_hi:[1,0]
	v_pk_mul_f32 v[8:9], v[26:27], v[0:1] op_sel_hi:[1,0]
	v_cvt_pk_bf16_f32 v6, v6, v7
	v_cvt_pk_bf16_f32 v7, v8, v9
	global_store_dwordx2 v[2:3], v[4:5], off offset:32
	global_store_dwordx2 v[2:3], v[6:7], off offset:96
	v_pk_mul_f32 v[4:5], v[44:45], v[0:1] op_sel_hi:[1,0]
	v_pk_mul_f32 v[6:7], v[46:47], v[0:1] op_sel_hi:[1,0]
	v_cvt_pk_bf16_f32 v4, v4, v5
	v_cvt_pk_bf16_f32 v5, v6, v7
	v_pk_mul_f32 v[6:7], v[28:29], v[0:1] op_sel_hi:[1,0]
	v_pk_mul_f32 v[8:9], v[30:31], v[0:1] op_sel_hi:[1,0]
	v_cvt_pk_bf16_f32 v6, v6, v7
	v_cvt_pk_bf16_f32 v7, v8, v9
	global_store_dwordx2 v[2:3], v[4:5], off offset:48
	global_store_dwordx2 v[2:3], v[6:7], off offset:112
	s_cbranch_scc1 .LBB0_523
